# np15 + nt cache policy on the read-once f32 loads of the ffn_w_in / ffn_w_out conversion loops
# speedup vs baseline: 1.0155x; 1.0039x over previous
.LBB0_1367:
	s_mul_hi_i32 s6, s17, 0x2e8ba2e9
	s_lshr_b32 s7, s6, 31
	s_ashr_i32 s6, s6, 2
	s_add_i32 s7, s6, s7
	s_lshl_b32 s6, s7, 6
	s_mulk_i32 s7, 0xea00
	s_add_i32 s8, s14, s7
	s_ashr_i32 s9, s8, 31
	v_or_b32_e32 v25, s6, v10
	v_lshl_add_u64 v[26:27], s[8:9], 2, v[6:7]
	v_add_u32_e32 v28, 8, v25
	v_or_b32_e32 v29, 16, v25
	v_add_u32_e32 v30, 24, v25
	v_or_b32_e32 v31, 32, v25
	v_add_u32_e32 v32, 40, v25
	v_or_b32_e32 v33, 48, v25
	v_add_u32_e32 v34, 56, v25
	v_mad_i64_i32 v[58:59], s[18:19], v25, s16, v[26:27]
	v_mad_i64_i32 v[60:61], s[18:19], v28, s16, v[26:27]
	v_mad_i64_i32 v[62:63], s[18:19], v29, s16, v[26:27]
	v_mad_i64_i32 v[64:65], s[18:19], v30, s16, v[26:27]
	v_mad_i64_i32 v[66:67], s[18:19], v31, s16, v[26:27]
	v_mad_i64_i32 v[68:69], s[18:19], v32, s16, v[26:27]
	v_mad_i64_i32 v[70:71], s[18:19], v33, s16, v[26:27]
	v_mad_i64_i32 v[72:73], s[18:19], v34, s16, v[26:27]
	global_load_dwordx4 v[26:29], v[58:59], off nt
	global_load_dwordx4 v[30:33], v[60:61], off nt
	global_load_dwordx4 v[34:37], v[62:63], off nt
	global_load_dwordx4 v[38:41], v[64:65], off nt
	global_load_dwordx4 v[42:45], v[66:67], off nt
	global_load_dwordx4 v[46:49], v[68:69], off nt
	global_load_dwordx4 v[50:53], v[70:71], off nt
	global_load_dwordx4 v[54:57], v[72:73], off nt
	v_add_u32_e32 v58, s8, v11
	v_ashrrev_i32_e32 v59, 31, v58
	v_lshlrev_b64 v[58:59], 11, v[58:59]
	s_ashr_i32 s7, s6, 31
	v_lshl_add_u64 v[58:59], s[4:5], 0, v[58:59]
	s_add_i32 s17, s17, s70
	s_add_i32 s14, s14, s15
	v_lshl_add_u64 v[58:59], s[6:7], 1, v[58:59]
	s_cmpk_gt_i32 s17, 0x15f
	v_lshl_add_u64 v[58:59], v[58:59], 0, v[2:3]
	s_waitcnt vmcnt(7)
	ds_write2_b32 v12, v26, v27 offset1:1
	ds_write2_b32 v12, v28, v29 offset0:2 offset1:3
	s_waitcnt vmcnt(6)
	ds_write2_b32 v5, v30, v31 offset1:1
	ds_write2_b32 v8, v32, v33 offset1:1
	s_waitcnt vmcnt(5)
	ds_write2_b32 v9, v34, v35 offset1:1
	ds_write2_b32 v14, v36, v37 offset1:1
	s_waitcnt vmcnt(4)
	ds_write2_b32 v15, v38, v39 offset1:1
	ds_write2_b32 v16, v40, v41 offset1:1
	s_waitcnt vmcnt(3)
	ds_write2_b32 v17, v42, v43 offset1:1
	ds_write2_b32 v18, v44, v45 offset1:1
	s_waitcnt vmcnt(2)
	ds_write2_b32 v19, v46, v47 offset1:1
	ds_write2_b32 v20, v48, v49 offset1:1
	s_waitcnt vmcnt(1)
	ds_write2_b32 v21, v50, v51 offset1:1
	ds_write2_b32 v22, v52, v53 offset1:1
	s_waitcnt vmcnt(0)
	ds_write2_b32 v23, v54, v55 offset1:1
	ds_write2_b32 v24, v56, v57 offset1:1
	s_waitcnt lgkmcnt(0)
	s_barrier
	ds_read_b32 v25, v13
	ds_read_b32 v26, v13 offset:1028
	ds_read_b32 v27, v13 offset:2056
	ds_read_b32 v28, v13 offset:3084
	ds_read_b32 v29, v13 offset:4112
	ds_read_b32 v30, v13 offset:5140
	ds_read_b32 v31, v13 offset:6168
	ds_read_b32 v32, v13 offset:7196
	ds_read_b32 v33, v13 offset:8224
	ds_read_b32 v34, v13 offset:9252
	ds_read_b32 v35, v13 offset:10280
	ds_read_b32 v36, v13 offset:11308
	ds_read_b32 v37, v13 offset:12336
	ds_read_b32 v38, v13 offset:13364
	ds_read_b32 v39, v13 offset:14392
	ds_read_b32 v40, v13 offset:15420
	ds_read_b32 v41, v13 offset:16448
	ds_read_b32 v42, v13 offset:17476
	ds_read_b32 v43, v13 offset:18504
	ds_read_b32 v44, v13 offset:19532
	ds_read_b32 v45, v13 offset:20560
	ds_read_b32 v46, v13 offset:21588
	ds_read_b32 v47, v13 offset:22616
	ds_read_b32 v48, v13 offset:23644
	ds_read_b32 v49, v13 offset:24672
	ds_read_b32 v50, v13 offset:25700
	ds_read_b32 v51, v13 offset:26728
	ds_read_b32 v52, v13 offset:27756
	ds_read_b32 v53, v13 offset:28784
	ds_read_b32 v54, v13 offset:29812
	ds_read_b32 v55, v13 offset:30840
	ds_read_b32 v56, v13 offset:31868
	s_waitcnt lgkmcnt(14)
	v_cvt_pk_bf16_f32 v26, v25, v26
	v_cvt_pk_bf16_f32 v27, v27, v28
	v_cvt_pk_bf16_f32 v28, v29, v30
	v_cvt_pk_bf16_f32 v29, v31, v32
	v_cvt_pk_bf16_f32 v30, v33, v34
	v_cvt_pk_bf16_f32 v31, v35, v36
	v_cvt_pk_bf16_f32 v32, v37, v38
	v_cvt_pk_bf16_f32 v33, v39, v40
	v_cvt_pk_bf16_f32 v34, v41, v42
	s_waitcnt lgkmcnt(12)
	v_cvt_pk_bf16_f32 v35, v43, v44
	s_waitcnt lgkmcnt(10)
	v_cvt_pk_bf16_f32 v36, v45, v46
	s_waitcnt lgkmcnt(8)
	v_cvt_pk_bf16_f32 v37, v47, v48
	s_waitcnt lgkmcnt(6)
	v_cvt_pk_bf16_f32 v38, v49, v50
	s_waitcnt lgkmcnt(4)
	v_cvt_pk_bf16_f32 v39, v51, v52
	s_waitcnt lgkmcnt(2)
	v_cvt_pk_bf16_f32 v40, v53, v54
	s_waitcnt lgkmcnt(0)
	v_cvt_pk_bf16_f32 v41, v55, v56
	global_store_dwordx4 v[58:59], v[26:29], off
	global_store_dwordx4 v[58:59], v[30:33], off offset:16
	global_store_dwordx4 v[58:59], v[34:37], off offset:32
	global_store_dwordx4 v[58:59], v[38:41], off offset:48
	s_barrier
	s_cbranch_scc0 .LBB0_1367

.LBB0_1458:
	s_addk_i32 s10, 0x80
	s_ashr_i32 s4, s10, 31
	s_lshr_b32 s4, s4, 30
	s_add_i32 s4, s10, s4
	s_ashr_i32 s5, s4, 2
	s_lshl_b32 s4, s5, 6
	s_lshl_b32 s5, s5, 10
	s_sub_i32 s8, s11, s5
	v_or_b32_e32 v26, s4, v8
	s_ashr_i32 s9, s8, 31
	v_ashrrev_i32_e32 v27, 31, v26
	v_or_b32_e32 v28, 16, v26
	v_or_b32_e32 v30, 32, v26
	v_or_b32_e32 v32, 48, v26
	v_lshl_add_u64 v[34:35], s[8:9], 2, v[4:5]
	v_lshlrev_b64 v[26:27], 12, v[26:27]
	v_lshl_add_u64 v[36:37], v[34:35], 0, v[26:27]
	v_add_co_u32_e32 v58, vcc, s12, v36
	v_ashrrev_i32_e32 v29, 31, v28
	s_nop 0
	v_addc_co_u32_e32 v59, vcc, 0, v37, vcc
	v_add_co_u32_e32 v62, vcc, s13, v36
	v_ashrrev_i32_e32 v31, 31, v30
	s_nop 0
	v_addc_co_u32_e32 v63, vcc, 0, v37, vcc
	v_add_co_u32_e32 v66, vcc, s14, v36
	v_ashrrev_i32_e32 v33, 31, v32
	s_nop 0
	v_addc_co_u32_e32 v67, vcc, 0, v37, vcc
	v_lshlrev_b64 v[38:39], 12, v[28:29]
	v_lshlrev_b64 v[30:31], 12, v[30:31]
	v_lshlrev_b64 v[32:33], 12, v[32:33]
	v_add_co_u32_e32 v70, vcc, s15, v36
	global_load_dwordx4 v[26:29], v[36:37], off nt
	v_lshl_add_u64 v[60:61], v[34:35], 0, v[38:39]
	v_lshl_add_u64 v[64:65], v[34:35], 0, v[30:31]
	v_lshl_add_u64 v[68:69], v[34:35], 0, v[32:33]
	v_addc_co_u32_e32 v71, vcc, 0, v37, vcc
	global_load_dwordx4 v[30:33], v[58:59], off nt
	global_load_dwordx4 v[34:37], v[60:61], off nt
	global_load_dwordx4 v[38:41], v[62:63], off nt
	global_load_dwordx4 v[42:45], v[64:65], off nt
	global_load_dwordx4 v[46:49], v[66:67], off nt
	global_load_dwordx4 v[50:53], v[68:69], off nt
	global_load_dwordx4 v[54:57], v[70:71], off nt
	v_add_u32_e32 v25, s8, v146
	v_mad_i64_i32 v[58:59], s[8:9], v25, s16, v[6:7]
	s_ashr_i32 s5, s4, 31
	s_add_i32 s11, s11, 0x8000
	v_lshl_add_u64 v[58:59], s[4:5], 1, v[58:59]
	s_cmp_lt_i32 s10, 48
	v_lshl_add_u64 v[58:59], v[58:59], 0, v[2:3]
	s_waitcnt vmcnt(0)
	ds_write2_b32 v9, v26, v27 offset1:1
	ds_write2_b32 v9, v28, v29 offset0:2 offset1:3
	ds_write2_b32 v10, v30, v31 offset1:1
	ds_write2_b32 v11, v32, v33 offset1:1
	ds_write2_b32 v12, v34, v35 offset1:1
	ds_write2_b32 v13, v36, v37 offset1:1
	ds_write2_b32 v14, v38, v39 offset1:1
	ds_write2_b32 v15, v40, v41 offset1:1
	ds_write2_b32 v16, v42, v43 offset1:1
	ds_write2_b32 v17, v44, v45 offset1:1
	ds_write2_b32 v18, v46, v47 offset1:1
	ds_write2_b32 v19, v48, v49 offset1:1
	ds_write2_b32 v20, v50, v51 offset1:1
	ds_write2_b32 v21, v52, v53 offset1:1
	ds_write2_b32 v22, v54, v55 offset1:1
	ds_write2_b32 v23, v56, v57 offset1:1
	s_waitcnt lgkmcnt(0)
	s_barrier
	ds_read_b32 v25, v24
	ds_read_b32 v26, v24 offset:1028
	ds_read_b32 v27, v24 offset:2056
	ds_read_b32 v28, v24 offset:3084
	ds_read_b32 v29, v24 offset:4112
	ds_read_b32 v30, v24 offset:5140
	ds_read_b32 v31, v24 offset:6168
	ds_read_b32 v32, v24 offset:7196
	ds_read_b32 v33, v24 offset:8224
	ds_read_b32 v34, v24 offset:9252
	ds_read_b32 v35, v24 offset:10280
	ds_read_b32 v36, v24 offset:11308
	ds_read_b32 v37, v24 offset:12336
	ds_read_b32 v38, v24 offset:13364
	ds_read_b32 v39, v24 offset:14392
	ds_read_b32 v40, v24 offset:15420
	ds_read_b32 v41, v24 offset:16448
	ds_read_b32 v42, v24 offset:17476
	ds_read_b32 v43, v24 offset:18504
	ds_read_b32 v44, v24 offset:19532
	ds_read_b32 v45, v24 offset:20560
	ds_read_b32 v46, v24 offset:21588
	ds_read_b32 v47, v24 offset:22616
	ds_read_b32 v48, v24 offset:23644
	ds_read_b32 v49, v24 offset:24672
	ds_read_b32 v50, v24 offset:25700
	ds_read_b32 v51, v24 offset:26728
	ds_read_b32 v52, v24 offset:27756
	ds_read_b32 v53, v24 offset:28784
	ds_read_b32 v54, v24 offset:29812
	ds_read_b32 v55, v24 offset:30840
	ds_read_b32 v56, v24 offset:31868
	s_waitcnt lgkmcnt(14)
	v_cvt_pk_bf16_f32 v26, v25, v26
	v_cvt_pk_bf16_f32 v27, v27, v28
	v_cvt_pk_bf16_f32 v28, v29, v30
	v_cvt_pk_bf16_f32 v29, v31, v32
	v_cvt_pk_bf16_f32 v30, v33, v34
	v_cvt_pk_bf16_f32 v31, v35, v36
	v_cvt_pk_bf16_f32 v32, v37, v38
	v_cvt_pk_bf16_f32 v33, v39, v40
	v_cvt_pk_bf16_f32 v34, v41, v42
	s_waitcnt lgkmcnt(12)
	v_cvt_pk_bf16_f32 v35, v43, v44
	s_waitcnt lgkmcnt(10)
	v_cvt_pk_bf16_f32 v36, v45, v46
	s_waitcnt lgkmcnt(8)
	v_cvt_pk_bf16_f32 v37, v47, v48
	s_waitcnt lgkmcnt(6)
	v_cvt_pk_bf16_f32 v38, v49, v50
	s_waitcnt lgkmcnt(4)
	v_cvt_pk_bf16_f32 v39, v51, v52
	s_waitcnt lgkmcnt(2)
	v_cvt_pk_bf16_f32 v40, v53, v54
	s_waitcnt lgkmcnt(0)
	v_cvt_pk_bf16_f32 v41, v55, v56
	global_store_dwordx4 v[58:59], v[26:29], off
	global_store_dwordx4 v[58:59], v[30:33], off offset:16
	global_store_dwordx4 v[58:59], v[34:37], off offset:32
	global_store_dwordx4 v[58:59], v[38:41], off offset:48
	s_barrier
	s_cbranch_scc1 .LBB0_1458
	s_sleep 127
	s_sleep 127
